# v075 with ssm step-3 stagger lengthened (sleep 45) and a step-1 stagger (sleep 12) for waves 4-7
# baseline (speedup 1.0000x reference)
;     __device__ __forceinline__ unsigned char* ws() const { return *(const __attribute__((address_space(4))) ucptr_t*)(p + 264); }
; #define LAUNDER(Fx) Ctx Fx = F; asm volatile("" : "+v"(Fx.tid)); Fx.lane = Fx.tid & 63; Fx.wave = __builtin_amdgcn_readfirstlane(Fx.tid >> 6)
; __device__ __forceinline__ void ssm_v2(const KA& A, const Ctx& F, int l, int b, int g) {
;     bf16* PS = (bf16*)(F.ws + WS_PS);
;     float* ZF = (float*)F.lds;
;     const unsigned char* base = F.ws + WS_SSM + (size_t)(l * 16 + g) * SSG_BYTES;
;     const bf16* TM = (const bf16*)(base + SSG_TM); const bf16* GM = (const bf16*)(base + SSG_GM); const bf16* HM = (const bf16*)(base + SSG_HM); const float* lam = (const float*)(base + SSG_LAM);
;     const int lane = F.lane, w = F.wave, r32 = lane & 31, hh = lane >> 5;
;     const size_t tok0 = (size_t)b * SEQ + 512 * w;
;     bf16x8_t uf[16];
;     { const bf16* up = PS + (tok0 + 16 * r32) * PSW + C_SSM + 16 * g + 8 * hh;
; #pragma unroll
;       for (int s = 0; s < 16; ++s) uf[s] = *(const bf16x8_t*)(up + (size_t)s * PSW); }
; __device__ __forceinline__ void run_phase(const KA& A, const Ctx& F, int ph) {
;     ...
;         { LAUNDER(F1);
;           if (F1.bid < 48) { if (p3m & 1) rwkv_scan(A, F1, l, F1.bid / 6, F1.bid % 6); }
;           else if (F1.bid < 176) { if (p3m & 2) { const int it = F1.bid - 48; ssm_v2(A, F1, l, it / 16, it % 16); } } }
.LBB0_169:
	s_and_b64 vcc, exec, s[2:3]
	s_cbranch_vccz .LBB0_216
	s_cmp_gt_i32 s25, 1
	s_mov_b64 s[0:1], -1
	s_cbranch_scc0 .LBB0_214
	v_mov_b32_e32 v130, v242
	v_writelane_b32 v255, s4, 40
	v_readfirstlane_b32 s2, v130
	s_ashr_i32 s6, s2, 6
	v_writelane_b32 v255, s5, 41
	v_and_b32_e32 v114, 63, v130
	s_cmp_gt_i32 s80, 47
	s_mov_b64 s[34:35], 0x2000
	s_cbranch_scc0 .LBB0_182
	s_cmpk_gt_u32 s80, 0xaf
	s_cbranch_scc1 .LBB0_181
	s_lshl_b32 s0, s80, 8
	s_and_b32 s0, s0, 0xf000
	s_lshl_b32 s1, s6, 9
	s_lshl_b32 s3, s79, 4
	s_and_b32 s4, s80, 15
	s_addk_i32 s0, 0xd000
	s_ashr_i32 s5, s1, 31
	v_and_b32_e32 v85, 31, v130
	s_add_u32 s8, s1, s0
	v_lshl_or_b32 v2, v85, 4, s8
	v_mov_b64_e32 v[0:1], s[82:83]
	s_addc_u32 s7, s5, 0
	v_mad_u64_u32 v[0:1], s[0:1], v2, s92, v[0:1]
	v_lshrrev_b32_e32 v84, 5, v114
	v_mad_i32_i24 v1, s7, v236, v1
	s_lshl_b32 s0, s4, 5
	s_mov_b32 s1, s24
	v_lshl_add_u64 v[0:1], v[0:1], 0, s[0:1]
	v_lshlrev_b32_e32 v80, 4, v84
	v_lshl_add_u64 v[0:1], v[0:1], 0, v[80:81]
	v_add_co_u32_e32 v2, vcc, s66, v0
	s_movk_i32 s0, 0x2000
	s_nop 0
	v_addc_co_u32_e32 v3, vcc, 0, v1, vcc
	v_add_co_u32_e32 v4, vcc, s0, v0
	s_movk_i32 s0, 0x5000
	s_nop 0
	v_addc_co_u32_e32 v5, vcc, 0, v1, vcc
	global_load_dwordx4 v[20:23], v[2:3], off offset:1024
	global_load_dwordx4 v[24:27], v[4:5], off offset:2560
	v_add_co_u32_e32 v2, vcc, s73, v0
	s_lshl_b32 s9, s4, 4
	s_nop 0
	v_addc_co_u32_e32 v3, vcc, 0, v1, vcc
	v_add_co_u32_e32 v4, vcc, s0, v0
	s_movk_i32 s0, 0x6000
	s_nop 0
	v_addc_co_u32_e32 v5, vcc, 0, v1, vcc
	global_load_dwordx4 v[28:31], v[2:3], off
	global_load_dwordx4 v[16:19], v[4:5], off offset:1536
	v_add_co_u32_e32 v2, vcc, s0, v0
	s_mov_b32 s0, 0x8000
	s_nop 0
	v_addc_co_u32_e32 v3, vcc, 0, v1, vcc
	v_add_co_u32_e32 v4, vcc, s0, v0
	s_mov_b32 s0, 0x9000
	s_nop 0
	v_addc_co_u32_e32 v5, vcc, 0, v1, vcc
	global_load_dwordx4 v[32:35], v[2:3], off offset:3072
	global_load_dwordx4 v[36:39], v[4:5], off offset:512
	v_add_co_u32_e32 v2, vcc, s0, v0
	s_mov_b32 s0, 0xa000
	s_nop 0
	v_addc_co_u32_e32 v3, vcc, 0, v1, vcc
	v_add_co_u32_e32 v4, vcc, s0, v0
	s_mov_b32 s0, 0xc000
	s_nop 0
	v_addc_co_u32_e32 v5, vcc, 0, v1, vcc
	global_load_dwordx4 v[52:55], v[2:3], off offset:2048
	global_load_dwordx4 v[48:51], v[4:5], off offset:3584
	v_add_co_u32_e32 v2, vcc, s0, v0
	s_mov_b32 s0, 0xd000
	s_nop 0
	v_addc_co_u32_e32 v3, vcc, 0, v1, vcc
	v_add_co_u32_e32 v4, vcc, s0, v0
	s_mov_b32 s0, 0xf000
	s_nop 0
	v_addc_co_u32_e32 v5, vcc, 0, v1, vcc
	global_load_dwordx4 v[40:43], v[2:3], off offset:1024
	global_load_dwordx4 v[44:47], v[4:5], off offset:2560
	v_add_co_u32_e32 v2, vcc, s0, v0
	s_mov_b32 s0, 0x10000
	s_nop 0
	v_addc_co_u32_e32 v3, vcc, 0, v1, vcc
	v_add_co_u32_e32 v4, vcc, s0, v0
	s_mov_b32 s0, 0x11000
	s_nop 0
	v_addc_co_u32_e32 v5, vcc, 0, v1, vcc
	global_load_dwordx4 v[56:59], v[2:3], off
	global_load_dwordx4 v[60:63], v[4:5], off offset:1536
	v_add_co_u32_e32 v2, vcc, s0, v0
	s_mov_b32 s0, 0x13000
	s_nop 0
	v_addc_co_u32_e32 v3, vcc, 0, v1, vcc
	v_add_co_u32_e32 v4, vcc, s0, v0
	s_mov_b32 s0, 0x14000
	s_nop 0
	v_addc_co_u32_e32 v5, vcc, 0, v1, vcc
	global_load_dwordx4 v[64:67], v[2:3], off offset:3072
	global_load_dwordx4 v[68:71], v[4:5], off offset:512
	v_add_co_u32_e32 v2, vcc, s0, v0
	s_mov_b32 s0, 0x15000
	s_nop 0
	v_addc_co_u32_e32 v3, vcc, 0, v1, vcc
	v_add_co_u32_e32 v0, vcc, s0, v0
	s_mul_i32 s0, s6, 0x4200
	s_nop 0
	v_addc_co_u32_e32 v1, vcc, 0, v1, vcc
	global_load_dwordx4 v[76:79], v[2:3], off offset:2048
	global_load_dwordx4 v[72:75], v[0:1], off offset:3584
	s_or_b32 s4, s3, s4
	v_readlane_b32 s12, v253, 60
	v_mov_b32_e32 v0, s0
	s_movk_i32 s0, 0x840
	s_mul_hi_i32 s3, s4, 0x40400
	s_mul_i32 s4, s4, 0x40400
	v_readlane_b32 s14, v253, 62
	v_mad_u32_u24 v0, v84, s0, v0
	v_readlane_b32 s15, v253, 63
	s_add_u32 s0, s14, s4
	v_lshlrev_b32_e32 v1, 2, v85
	v_lshlrev_b32_e32 v80, 4, v114
	s_addc_u32 s1, s15, s3
	v_lshlrev_b32_e32 v86, 3, v84
	v_add3_u32 v87, v0, v1, 0
	v_lshl_add_u64 v[82:83], s[0:1], 0, v[80:81]
	s_mov_b64 s[0:1], 0
	v_readlane_b32 s13, v253, 61
	s_cmp_lt_u32 s6, 4
	s_cbranch_scc1 .Lssm_nostag1
	s_sleep 12
; __device__ __forceinline__ int crow16(int g, int hh) { return (g & 3) + 8 * (g >> 2) + 4 * hh; }
; __device__ __forceinline__ void ssm_v2(const KA& A, const Ctx& F, int l, int b, int g) {
;     ...
;     for (int nt = 0; nt < ((sp_ & 1) ? 4 : 0); ++nt) {
;         f32x16 acc = {};
;         const bf16* gp = GM + (size_t)(nt * 16 * 64 + lane) * 8;
;         bf16x8_t gf[16];
; #pragma unroll
;         for (int s = 0; s < 16; ++s) gf[s] = *(const bf16x8_t*)(gp + s * 512);
;         asm volatile("" :: "v"(gf[0]), "v"(gf[1]), "v"(gf[2]), "v"(gf[3]), "v"(gf[4]), "v"(gf[5]), "v"(gf[6]), "v"(gf[7]));
;         asm volatile("" :: "v"(gf[8]), "v"(gf[9]), "v"(gf[10]), "v"(gf[11]), "v"(gf[12]), "v"(gf[13]), "v"(gf[14]), "v"(gf[15]));
; #pragma unroll
;         for (int s = 0; s < 16; ++s) acc = __builtin_amdgcn_mfma_f32_32x32x16_bf16(uf[s], gf[s], acc, 0, 0, 0);
; #pragma unroll
;         for (int q = 0; q < 16; ++q) ZF[(32 * w + crow16(q, hh)) * ZS + 32 * nt + r32] = acc[q];
;     }
;     __syncthreads();
;     if (w == 0 && (sp_ & 2)) { const float lr = lam[lane], li = lam[64 + lane]; float xr = 0.f, xi = 0.f;
.Lssm_nostag1:
.LBB0_174:
	v_lshl_add_u64 v[4:5], v[82:83], 0, s[0:1]
	v_add_co_u32_e32 v6, vcc, 0x1f120000, v4
	s_add_u32 s0, s0, 0x4000
	s_nop 0
	v_addc_co_u32_e32 v7, vcc, 0, v5, vcc
	global_load_dwordx4 v[0:3], v[6:7], off
	global_load_dwordx4 v[88:91], v[6:7], off offset:1024
	global_load_dwordx4 v[92:95], v[6:7], off offset:2048
	global_load_dwordx4 v[96:99], v[6:7], off offset:3072
	v_add_co_u32_e32 v6, vcc, 0x1f121000, v4
	s_addc_u32 s1, s1, 0
	s_nop 0
	v_addc_co_u32_e32 v7, vcc, 0, v5, vcc
	global_load_dwordx4 v[100:103], v[6:7], off
	global_load_dwordx4 v[104:107], v[6:7], off offset:1024
	global_load_dwordx4 v[108:111], v[6:7], off offset:2048
	global_load_dwordx4 v[116:119], v[6:7], off offset:3072
	v_add_co_u32_e32 v6, vcc, 0x1f122000, v4
	s_cmp_eq_u32 s0, 0x10000
	s_nop 0
	v_addc_co_u32_e32 v7, vcc, 0, v5, vcc
	global_load_dwordx4 v[120:123], v[6:7], off
	global_load_dwordx4 v[124:127], v[6:7], off offset:1024
	global_load_dwordx4 v[132:135], v[6:7], off offset:2048
	global_load_dwordx4 v[136:139], v[6:7], off offset:3072
	v_add_co_u32_e32 v4, vcc, 0x1f123000, v4
	s_nop 1
	v_addc_co_u32_e32 v5, vcc, 0, v5, vcc
	global_load_dwordx4 v[140:143], v[4:5], off
	global_load_dwordx4 v[144:147], v[4:5], off offset:1024
	global_load_dwordx4 v[148:151], v[4:5], off offset:2048
	global_load_dwordx4 v[152:155], v[4:5], off offset:3072
	s_waitcnt vmcnt(8)
	v_mfma_f32_32x32x16_bf16 v[0:15], v[20:23], v[0:3], 0
	s_waitcnt vmcnt(0)
	v_mfma_f32_32x32x16_bf16 v[0:15], v[24:27], v[88:91], v[0:15]
	v_mfma_f32_32x32x16_bf16 v[0:15], v[28:31], v[92:95], v[0:15]
	v_mfma_f32_32x32x16_bf16 v[0:15], v[16:19], v[96:99], v[0:15]
	v_mfma_f32_32x32x16_bf16 v[0:15], v[32:35], v[100:103], v[0:15]
	v_mfma_f32_32x32x16_bf16 v[0:15], v[36:39], v[104:107], v[0:15]
	v_mfma_f32_32x32x16_bf16 v[0:15], v[52:55], v[108:111], v[0:15]
	v_mfma_f32_32x32x16_bf16 v[0:15], v[48:51], v[116:119], v[0:15]
	v_mfma_f32_32x32x16_bf16 v[0:15], v[40:43], v[120:123], v[0:15]
	v_mfma_f32_32x32x16_bf16 v[0:15], v[44:47], v[124:127], v[0:15]
	v_mfma_f32_32x32x16_bf16 v[0:15], v[56:59], v[132:135], v[0:15]
	v_mfma_f32_32x32x16_bf16 v[0:15], v[60:63], v[136:139], v[0:15]
	v_mfma_f32_32x32x16_bf16 v[0:15], v[64:67], v[140:143], v[0:15]
	v_mfma_f32_32x32x16_bf16 v[0:15], v[68:71], v[144:147], v[0:15]
	v_mfma_f32_32x32x16_bf16 v[0:15], v[76:79], v[148:151], v[0:15]
	v_mfma_f32_32x32x16_bf16 v[0:15], v[72:75], v[152:155], v[0:15]
	s_nop 11
	ds_write2_b32 v87, v0, v1 offset1:132
	v_add_u32_e32 v0, 0x400, v87
	ds_write2_b32 v0, v2, v3 offset0:8 offset1:140
	v_add_u32_e32 v0, 0x1000, v87
	ds_write2_b32 v0, v4, v5 offset0:32 offset1:164
	v_add_u32_e32 v0, 0x1400, v87
	ds_write2_b32 v0, v6, v7 offset0:40 offset1:172
	v_add_u32_e32 v0, 0x2000, v87
	ds_write2_b32 v0, v8, v9 offset0:64 offset1:196
	v_add_u32_e32 v0, 0x2400, v87
	ds_write2_b32 v0, v10, v11 offset0:72 offset1:204
	v_add_u32_e32 v0, 0x3000, v87
	ds_write2_b32 v0, v12, v13 offset0:96 offset1:228
	v_add_u32_e32 v0, 0x3400, v87
	v_add_u32_e32 v87, 0x80, v87
	ds_write2_b32 v0, v14, v15 offset0:104 offset1:236
	s_cbranch_scc0 .LBB0_174
	v_readlane_b32 s12, v253, 60
	v_readlane_b32 s14, v253, 62
	v_readlane_b32 s15, v253, 63
	s_add_u32 s0, s14, s4
	s_addc_u32 s1, s15, s3
	s_add_u32 s4, s0, 0x1f100000
	s_addc_u32 s5, s1, 0
	s_cmp_lt_u32 s2, 64
	s_mov_b64 s[0:1], -1
	v_readlane_b32 s13, v253, 61
	s_waitcnt lgkmcnt(0)
	s_barrier
	s_cbranch_scc1 .LBB0_177
	v_mov_b32_e32 v115, v81
	s_mov_b64 s[0:1], 0

; __device__ __forceinline__ void ssm_v2(const KA& A, const Ctx& F, int l, int b, int g) {
;     ...
;     for (int nt = 0; nt < 8; ++nt) if (sp_ & 4) {
;         f32x16 acc = {};
;         const bf16* tp = TM + (size_t)(nt * 16 * 64 + lane) * 8; const bf16* hp = HM + (size_t)(nt * 8 * 64 + lane) * 8;
;         { bf16x8_t tf[16], hf[8];
; #pragma unroll
;           for (int s = 0; s < 16; ++s) if (s <= 2 * nt + 1) tf[s] = *(const bf16x8_t*)(tp + s * 512);
; #pragma unroll
;           for (int s = 0; s < 8; ++s) hf[s] = *(const bf16x8_t*)(hp + s * 512);
.LBB0_180:
	v_lshlrev_b64 v[0:1], 4, v[114:115]
	v_lshl_add_u64 v[2:3], s[4:5], 0, v[0:1]
	s_waitcnt lgkmcnt(0)
	s_barrier
	global_load_dwordx4 v[124:127], v[2:3], off
	global_load_dwordx4 v[132:135], v[2:3], off offset:1024
	s_add_u32 s2, s4, 0x30000
	s_addc_u32 s3, s5, 0
	v_lshl_add_u64 v[0:1], s[2:3], 0, v[0:1]
	global_load_dwordx4 v[136:139], v[0:1], off
	global_load_dwordx4 v[140:143], v[0:1], off offset:1024
	global_load_dwordx4 v[144:147], v[0:1], off offset:2048
	global_load_dwordx4 v[148:151], v[0:1], off offset:3072
	v_add_co_u32_e32 v0, vcc, s66, v0
	v_lshl_or_b32 v2, s6, 5, v85
	s_nop 0
	v_addc_co_u32_e32 v1, vcc, 0, v1, vcc
	global_load_dwordx4 v[152:155], v[0:1], off
	global_load_dwordx4 v[156:159], v[0:1], off offset:1024
	global_load_dwordx4 v[160:163], v[0:1], off offset:2048
	global_load_dwordx4 v[164:167], v[0:1], off offset:3072
	s_cmp_lt_u32 s6, 4
	s_cbranch_scc1 .Lssm_nostag
	s_sleep 45
